# combined: carry-loop batching + attention row-sum with two alternating accumulators (no hazard nops) + accumulator zeroing via v_mov_b64 + hot loop heads aligned to 64 B
# speedup vs baseline: 1.0064x; 1.0049x over previous
;     ...
;     f32x4 acc[2][2][4][2];
; #pragma unroll
;     for (int a = 0; a < 2; ++a)
; #pragma unroll
;         for (int b = 0; b < 2; ++b)
; #pragma unroll
;             for (int m = 0; m < 4; ++m)
; #pragma unroll
;                 for (int n = 0; n < 2; ++n) acc[a][b][m][n] = (f32x4){0.f, 0.f, 0.f, 0.f};
;     ...
;     for (;;) {
;         const bool has_next = S.next(ui + 1, nxt);
;         const char* nA = has_next ? PG8_ABASE(nxt) : cA; const char* nB = has_next ? (const char*)g.Bt + (size_t)nxt.pn * tstepB : cB;
; #pragma unroll 1
;         for (int t = 0; t < nt; t += 2) {
;             const bool last = (t == nt - 2);
;             const char* a1 = cA + (size_t)(t + 1) * kstep;
;             const char* a2 = last ? nA : cA + (size_t)(t + 2) * kstep; const char* b2 = last ? nB : cB + (size_t)(t + 2) * kstep;
;             const char* a3 = a2 + kstep; const char* b3 = b2 + kstep;
.LBB0_164:
	v_lshl_add_u64 v[6:7], v[148:149], 0, s[52:53]
	v_lshl_add_u64 v[154:155], v[4:5], 0, s[4:5]
	v_mov_b32_e32 v4, 0
	v_lshl_add_u64 v[150:151], v[6:7], 0, v[140:141]
	v_lshl_add_u64 v[152:153], v[6:7], 0, v[142:143]
	s_mov_b32 s60, -2
	s_mov_b64 s[38:39], 0
	v_mov_b32_e32 v5, v4
	v_mov_b64_e32 v[6:7], v[4:5]
	v_mov_b64_e32 v[8:9], v[4:5]
	v_mov_b64_e32 v[10:11], v[4:5]
	v_mov_b64_e32 v[20:21], v[4:5]
	v_mov_b64_e32 v[22:23], v[4:5]
	v_mov_b64_e32 v[24:25], v[4:5]
	v_mov_b64_e32 v[26:27], v[4:5]
	v_mov_b64_e32 v[36:37], v[4:5]
	v_mov_b64_e32 v[38:39], v[4:5]
	v_mov_b64_e32 v[40:41], v[4:5]
	v_mov_b64_e32 v[42:43], v[4:5]
	v_mov_b64_e32 v[52:53], v[4:5]
	v_mov_b64_e32 v[54:55], v[4:5]
	v_mov_b64_e32 v[56:57], v[4:5]
	v_mov_b64_e32 v[58:59], v[4:5]
	v_mov_b64_e32 v[12:13], v[4:5]
	v_mov_b64_e32 v[14:15], v[4:5]
	v_mov_b64_e32 v[16:17], v[4:5]
	v_mov_b64_e32 v[18:19], v[4:5]
	v_mov_b64_e32 v[28:29], v[4:5]
	v_mov_b64_e32 v[30:31], v[4:5]
	v_mov_b64_e32 v[32:33], v[4:5]
	v_mov_b64_e32 v[34:35], v[4:5]
	v_mov_b64_e32 v[44:45], v[4:5]
	v_mov_b64_e32 v[46:47], v[4:5]
	v_mov_b64_e32 v[48:49], v[4:5]
	v_mov_b64_e32 v[50:51], v[4:5]
	v_mov_b64_e32 v[60:61], v[4:5]
	v_mov_b64_e32 v[62:63], v[4:5]
	v_mov_b64_e32 v[64:65], v[4:5]
	v_mov_b64_e32 v[66:67], v[4:5]
	v_mov_b64_e32 v[68:69], v[4:5]
	v_mov_b64_e32 v[70:71], v[4:5]
	v_mov_b64_e32 v[72:73], v[4:5]
	v_mov_b64_e32 v[74:75], v[4:5]
	v_mov_b64_e32 v[84:85], v[4:5]
	v_mov_b64_e32 v[86:87], v[4:5]
	v_mov_b64_e32 v[88:89], v[4:5]
	v_mov_b64_e32 v[90:91], v[4:5]
	v_mov_b64_e32 v[100:101], v[4:5]
	v_mov_b64_e32 v[102:103], v[4:5]
	v_mov_b64_e32 v[104:105], v[4:5]
	v_mov_b64_e32 v[106:107], v[4:5]
	v_mov_b64_e32 v[116:117], v[4:5]
	v_mov_b64_e32 v[118:119], v[4:5]
	v_mov_b64_e32 v[120:121], v[4:5]
	v_mov_b64_e32 v[122:123], v[4:5]
	v_mov_b64_e32 v[76:77], v[4:5]
	v_mov_b64_e32 v[78:79], v[4:5]
	v_mov_b64_e32 v[80:81], v[4:5]
	v_mov_b64_e32 v[82:83], v[4:5]
	v_mov_b64_e32 v[92:93], v[4:5]
	v_mov_b64_e32 v[94:95], v[4:5]
	v_mov_b64_e32 v[96:97], v[4:5]
	v_mov_b64_e32 v[98:99], v[4:5]
	v_mov_b64_e32 v[108:109], v[4:5]
	v_mov_b64_e32 v[110:111], v[4:5]
	v_mov_b64_e32 v[112:113], v[4:5]
	v_mov_b64_e32 v[114:115], v[4:5]
	v_mov_b64_e32 v[124:125], v[4:5]
	v_mov_b64_e32 v[126:127], v[4:5]
	v_mov_b64_e32 v[128:129], v[4:5]
	v_mov_b64_e32 v[130:131], v[4:5]
	v_add_u32_e32 v246, 0x10000, v158
	v_add_u32_e32 v247, 0x14000, v158
	v_add_u32_e32 v248, 0x18000, v158
	v_add_u32_e32 v249, 0x1c000, v158
	.p2align 6

;     ...
; #pragma unroll
;         for (int a = 0; a < 2; ++a)
; #pragma unroll
;             for (int b = 0; b < 2; ++b)
; #pragma unroll
;                 for (int m = 0; m < 4; ++m)
; #pragma unroll
;                     for (int n = 0; n < 2; ++n) acc[a][b][m][n] = (f32x4){0.f, 0.f, 0.f, 0.f};
;         cur = nxt; cA = nA; cB = nB; ++ui;
.LBB0_415:
	v_mov_b32_e32 v4, 0
	s_mov_b64 s[44:45], 0
	s_mov_b64 s[28:29], -1
	s_mov_b64 s[34:35], 0
	v_mov_b32_e32 v5, v4
	v_mov_b64_e32 v[6:7], v[4:5]
	v_mov_b64_e32 v[12:13], v[4:5]
	v_mov_b64_e32 v[14:15], v[4:5]
	v_mov_b64_e32 v[44:45], v[4:5]
	v_mov_b64_e32 v[46:47], v[4:5]
	v_mov_b64_e32 v[52:53], v[4:5]
	v_mov_b64_e32 v[54:55], v[4:5]
	v_mov_b64_e32 v[60:61], v[4:5]
	v_mov_b64_e32 v[62:63], v[4:5]
	v_mov_b64_e32 v[68:69], v[4:5]
	v_mov_b64_e32 v[70:71], v[4:5]
	v_mov_b64_e32 v[76:77], v[4:5]
	v_mov_b64_e32 v[78:79], v[4:5]
	v_mov_b64_e32 v[84:85], v[4:5]
	v_mov_b64_e32 v[86:87], v[4:5]
	v_mov_b64_e32 v[8:9], v[4:5]
	v_mov_b64_e32 v[10:11], v[4:5]
	v_mov_b64_e32 v[16:17], v[4:5]
	v_mov_b64_e32 v[18:19], v[4:5]
	v_mov_b64_e32 v[48:49], v[4:5]
	v_mov_b64_e32 v[50:51], v[4:5]
	v_mov_b64_e32 v[56:57], v[4:5]
	v_mov_b64_e32 v[58:59], v[4:5]
	v_mov_b64_e32 v[64:65], v[4:5]
	v_mov_b64_e32 v[66:67], v[4:5]
	v_mov_b64_e32 v[72:73], v[4:5]
	v_mov_b64_e32 v[74:75], v[4:5]
	v_mov_b64_e32 v[80:81], v[4:5]
	v_mov_b64_e32 v[82:83], v[4:5]
	v_mov_b64_e32 v[88:89], v[4:5]
	v_mov_b64_e32 v[90:91], v[4:5]
	v_mov_b64_e32 v[92:93], v[4:5]
	v_mov_b64_e32 v[94:95], v[4:5]
	v_mov_b64_e32 v[100:101], v[4:5]
	v_mov_b64_e32 v[102:103], v[4:5]
	v_mov_b64_e32 v[108:109], v[4:5]
	v_mov_b64_e32 v[110:111], v[4:5]
	v_mov_b64_e32 v[116:117], v[4:5]
	v_mov_b64_e32 v[118:119], v[4:5]
	v_mov_b64_e32 v[124:125], v[4:5]
	v_mov_b64_e32 v[126:127], v[4:5]
	v_mov_b64_e32 v[132:133], v[4:5]
	v_mov_b64_e32 v[134:135], v[4:5]
	v_mov_b64_e32 v[140:141], v[4:5]
	v_mov_b64_e32 v[142:143], v[4:5]
	v_mov_b64_e32 v[148:149], v[4:5]
	v_mov_b64_e32 v[150:151], v[4:5]
	v_mov_b64_e32 v[96:97], v[4:5]
	v_mov_b64_e32 v[98:99], v[4:5]
	v_mov_b64_e32 v[104:105], v[4:5]
	v_mov_b64_e32 v[106:107], v[4:5]
	v_mov_b64_e32 v[112:113], v[4:5]
	v_mov_b64_e32 v[114:115], v[4:5]
	v_mov_b64_e32 v[120:121], v[4:5]
	v_mov_b64_e32 v[122:123], v[4:5]
	v_mov_b64_e32 v[128:129], v[4:5]
	v_mov_b64_e32 v[130:131], v[4:5]
	v_mov_b64_e32 v[136:137], v[4:5]
	v_mov_b64_e32 v[138:139], v[4:5]
	v_mov_b64_e32 v[144:145], v[4:5]
	v_mov_b64_e32 v[146:147], v[4:5]
	v_mov_b64_e32 v[152:153], v[4:5]
	v_mov_b64_e32 v[154:155], v[4:5]
	.p2align 6

;     ...
;     for (;;) {
;         const bool has_next = S.next(ui + 1, nxt);
;         const char* nA = has_next ? PG8_ABASE(nxt) : cA; const char* nB = has_next ? (const char*)g.Bt + (size_t)nxt.pn * tstepB : cB;
; #pragma unroll 1
;         for (int t = 0; t < nt; t += 2) {
;             const bool last = (t == nt - 2);
;             const char* a1 = cA + (size_t)(t + 1) * kstep;
;             const char* a2 = last ? nA : cA + (size_t)(t + 2) * kstep; const char* b2 = last ? nB : cB + (size_t)(t + 2) * kstep;
;             const char* a3 = a2 + kstep; const char* b3 = b2 + kstep;
;     ...
; #pragma unroll
;         for (int a = 0; a < 2; ++a)
; #pragma unroll
;             for (int b = 0; b < 2; ++b)
; #pragma unroll
;                 for (int m = 0; m < 4; ++m)
; #pragma unroll
;                     for (int n = 0; n < 2; ++n) acc[a][b][m][n] = (f32x4){0.f, 0.f, 0.f, 0.f};
.LBB0_439:
	v_lshl_add_u64 v[6:7], v[180:181], 0, s[52:53]
	v_mov_b32_e32 v36, 0
	v_lshl_add_u64 v[182:183], v[6:7], 0, v[172:173]
	v_lshl_add_u64 v[184:185], v[6:7], 0, v[174:175]
	v_lshl_add_u64 v[186:187], v[4:5], 0, s[4:5]
	s_mov_b32 s62, -2
	s_mov_b64 s[38:39], 0
	v_mov_b32_e32 v37, v36
	v_mov_b64_e32 v[38:39], v[36:37]
	v_mov_b64_e32 v[40:41], v[36:37]
	v_mov_b64_e32 v[42:43], v[36:37]
	v_mov_b64_e32 v[48:49], v[36:37]
	v_mov_b64_e32 v[50:51], v[36:37]
	v_mov_b64_e32 v[56:57], v[36:37]
	v_mov_b64_e32 v[58:59], v[36:37]
	v_mov_b64_e32 v[64:65], v[36:37]
	v_mov_b64_e32 v[66:67], v[36:37]
	v_mov_b64_e32 v[72:73], v[36:37]
	v_mov_b64_e32 v[74:75], v[36:37]
	v_mov_b64_e32 v[80:81], v[36:37]
	v_mov_b64_e32 v[82:83], v[36:37]
	v_mov_b64_e32 v[88:89], v[36:37]
	v_mov_b64_e32 v[90:91], v[36:37]
	v_mov_b64_e32 v[44:45], v[36:37]
	v_mov_b64_e32 v[46:47], v[36:37]
	v_mov_b64_e32 v[52:53], v[36:37]
	v_mov_b64_e32 v[54:55], v[36:37]
	v_mov_b64_e32 v[60:61], v[36:37]
	v_mov_b64_e32 v[62:63], v[36:37]
	v_mov_b64_e32 v[68:69], v[36:37]
	v_mov_b64_e32 v[70:71], v[36:37]
	v_mov_b64_e32 v[76:77], v[36:37]
	v_mov_b64_e32 v[78:79], v[36:37]
	v_mov_b64_e32 v[84:85], v[36:37]
	v_mov_b64_e32 v[86:87], v[36:37]
	v_mov_b64_e32 v[92:93], v[36:37]
	v_mov_b64_e32 v[94:95], v[36:37]
	v_mov_b64_e32 v[96:97], v[36:37]
	v_mov_b64_e32 v[98:99], v[36:37]
	v_mov_b64_e32 v[100:101], v[36:37]
	v_mov_b64_e32 v[102:103], v[36:37]
	v_mov_b64_e32 v[104:105], v[36:37]
	v_mov_b64_e32 v[106:107], v[36:37]
	v_mov_b64_e32 v[112:113], v[36:37]
	v_mov_b64_e32 v[114:115], v[36:37]
	v_mov_b64_e32 v[120:121], v[36:37]
	v_mov_b64_e32 v[122:123], v[36:37]
	v_mov_b64_e32 v[128:129], v[36:37]
	v_mov_b64_e32 v[130:131], v[36:37]
	v_mov_b64_e32 v[136:137], v[36:37]
	v_mov_b64_e32 v[138:139], v[36:37]
	v_mov_b64_e32 v[144:145], v[36:37]
	v_mov_b64_e32 v[146:147], v[36:37]
	v_mov_b64_e32 v[152:153], v[36:37]
	v_mov_b64_e32 v[154:155], v[36:37]
	v_mov_b64_e32 v[108:109], v[36:37]
	v_mov_b64_e32 v[110:111], v[36:37]
	v_mov_b64_e32 v[116:117], v[36:37]
	v_mov_b64_e32 v[118:119], v[36:37]
	v_mov_b64_e32 v[124:125], v[36:37]
	v_mov_b64_e32 v[126:127], v[36:37]
	v_mov_b64_e32 v[132:133], v[36:37]
	v_mov_b64_e32 v[134:135], v[36:37]
	v_mov_b64_e32 v[140:141], v[36:37]
	v_mov_b64_e32 v[142:143], v[36:37]
	v_mov_b64_e32 v[148:149], v[36:37]
	v_mov_b64_e32 v[150:151], v[36:37]
	v_mov_b64_e32 v[156:157], v[36:37]
	v_mov_b64_e32 v[158:159], v[36:37]
	v_mov_b64_e32 v[160:161], v[36:37]
	v_mov_b64_e32 v[162:163], v[36:37]
	v_add_u32_e32 v204, 0x10000, v210
	v_add_u32_e32 v205, 0x14000, v210
	v_add_u32_e32 v206, 0x18000, v210
	v_add_u32_e32 v207, 0x1c000, v210
	.p2align 6

;     ...
; #pragma unroll
;         for (int a = 0; a < 2; ++a)
; #pragma unroll
;             for (int b = 0; b < 2; ++b)
; #pragma unroll
;                 for (int m = 0; m < 4; ++m)
; #pragma unroll
;                     for (int n = 0; n < 2; ++n) acc[a][b][m][n] = (f32x4){0.f, 0.f, 0.f, 0.f};
;         cur = nxt; cA = nA; cB = nB; ++ui;
.LBB0_467:
	v_mov_b32_e32 v20, 0
	s_mov_b64 s[48:49], 0
	s_mov_b64 s[38:39], -1
	s_mov_b64 s[46:47], 0
	v_mov_b32_e32 v21, v20
	v_mov_b64_e32 v[22:23], v[20:21]
	v_mov_b64_e32 v[24:25], v[20:21]
	v_mov_b64_e32 v[26:27], v[20:21]
	v_mov_b64_e32 v[32:33], v[20:21]
	v_mov_b64_e32 v[34:35], v[20:21]
	v_mov_b64_e32 v[40:41], v[20:21]
	v_mov_b64_e32 v[42:43], v[20:21]
	v_mov_b64_e32 v[48:49], v[20:21]
	v_mov_b64_e32 v[50:51], v[20:21]
	v_mov_b64_e32 v[56:57], v[20:21]
	v_mov_b64_e32 v[58:59], v[20:21]
	v_mov_b64_e32 v[64:65], v[20:21]
	v_mov_b64_e32 v[66:67], v[20:21]
	v_mov_b64_e32 v[72:73], v[20:21]
	v_mov_b64_e32 v[74:75], v[20:21]
	v_mov_b64_e32 v[28:29], v[20:21]
	v_mov_b64_e32 v[30:31], v[20:21]
	v_mov_b64_e32 v[36:37], v[20:21]
	v_mov_b64_e32 v[38:39], v[20:21]
	v_mov_b64_e32 v[44:45], v[20:21]
	v_mov_b64_e32 v[46:47], v[20:21]
	v_mov_b64_e32 v[52:53], v[20:21]
	v_mov_b64_e32 v[54:55], v[20:21]
	v_mov_b64_e32 v[60:61], v[20:21]
	v_mov_b64_e32 v[62:63], v[20:21]
	v_mov_b64_e32 v[68:69], v[20:21]
	v_mov_b64_e32 v[70:71], v[20:21]
	v_mov_b64_e32 v[76:77], v[20:21]
	v_mov_b64_e32 v[78:79], v[20:21]
	v_mov_b64_e32 v[80:81], v[20:21]
	v_mov_b64_e32 v[82:83], v[20:21]
	v_mov_b64_e32 v[84:85], v[20:21]
	v_mov_b64_e32 v[86:87], v[20:21]
	v_mov_b64_e32 v[88:89], v[20:21]
	v_mov_b64_e32 v[90:91], v[20:21]
	v_mov_b64_e32 v[96:97], v[20:21]
	v_mov_b64_e32 v[98:99], v[20:21]
	v_mov_b64_e32 v[104:105], v[20:21]
	v_mov_b64_e32 v[106:107], v[20:21]
	v_mov_b64_e32 v[112:113], v[20:21]
	v_mov_b64_e32 v[114:115], v[20:21]
	v_mov_b64_e32 v[120:121], v[20:21]
	v_mov_b64_e32 v[122:123], v[20:21]
	v_mov_b64_e32 v[128:129], v[20:21]
	v_mov_b64_e32 v[130:131], v[20:21]
	v_mov_b64_e32 v[136:137], v[20:21]
	v_mov_b64_e32 v[138:139], v[20:21]
	v_mov_b64_e32 v[92:93], v[20:21]
	v_mov_b64_e32 v[94:95], v[20:21]
	v_mov_b64_e32 v[100:101], v[20:21]
	v_mov_b64_e32 v[102:103], v[20:21]
	v_mov_b64_e32 v[108:109], v[20:21]
	v_mov_b64_e32 v[110:111], v[20:21]
	v_mov_b64_e32 v[116:117], v[20:21]
	v_mov_b64_e32 v[118:119], v[20:21]
	v_mov_b64_e32 v[124:125], v[20:21]
	v_mov_b64_e32 v[126:127], v[20:21]
	v_mov_b64_e32 v[132:133], v[20:21]
	v_mov_b64_e32 v[134:135], v[20:21]
	v_mov_b64_e32 v[140:141], v[20:21]
	v_mov_b64_e32 v[142:143], v[20:21]
	v_mov_b64_e32 v[144:145], v[20:21]
	v_mov_b64_e32 v[146:147], v[20:21]
	.p2align 6

; template <int C_> __device__ __forceinline__ void fin_chunk(f32x16& p0, f32x16& p1, f32x2& s2, v6i& pf) {
;   f32x16& p = (C_ < 2) ? p0 : p1; constexpr int r0 = 8 * (C_ & 1), g0 = (C_ < 2 ? 0 : 4) + 2 * (C_ & 1);
; #pragma unroll
;   for (int r = r0; r < r0 + 8; ++r) p[r] = __builtin_amdgcn_exp2f(p[r]);
; #pragma unroll
;   for (int r = r0; r < r0 + 8; r += 2) s2 += (f32x2){p[r], p[r + 1]};
;   (void)pf; (void)g0;
; }
; __device__ __forceinline__ void fin_tail(const f32x2& s2, float alpha, float& l_reg) {
;   float ps = s2.x + s2.y;
;   { auto rr = __builtin_amdgcn_permlane32_swap(__float_as_uint(ps), __float_as_uint(ps), false, false);
;     ps = __uint_as_float(rr[0]) + __uint_as_float(rr[1]); }
;   l_reg = l_reg * alpha + ps;
; }
.LBB0_650:
	v_sub_co_u32_e64 v0, s[38:39], s62, 1
	s_and_b64 s[38:39], s[38:39], exec
	v_readfirstlane_b32 s9, v0
	s_cselect_b32 s60, 5, s9
	s_add_i32 s9, s62, 1
	s_cmp_lg_u32 s62, 5
	s_cselect_b32 s9, s9, 0
	s_lshl_b32 s61, s60, 13
	v_add_u32_e32 v2, s61, v239
	v_add_u32_e32 v250, s61, v240
	v_lshl_add_u32 v0, s62, 12, v238
	v_add_u32_e32 v1, v0, v231
	v_add_u32_e32 v0, v0, v232
	ds_read_b128 v[242:245], v1
	ds_read_b128 v[202:205], v1 offset:2048
	ds_read_b128 v[246:249], v0
	ds_read_b128 v[206:209], v0 offset:2048
	s_waitcnt lgkmcnt(4)
	v_mfma_f32_32x32x64_f8f6f4 v[132:147], v[116:123], v[148:155], v[68:83]
	v_exp_f32_e32 v100, v100
	v_exp_f32_e32 v101, v101
	v_exp_f32_e32 v102, v102
	v_exp_f32_e32 v103, v103
	v_exp_f32_e32 v104, v104
	v_exp_f32_e32 v105, v105
	v_exp_f32_e32 v106, v106
	v_exp_f32_e32 v107, v107
	v_pk_add_f32 v[0:1], v[100:101], v[102:103]
	v_pk_add_f32 v[252:253], v[104:105], v[106:107]
	v_mfma_f32_32x32x64_f8f6f4 v[116:131], v[188:195], v[148:155], v[68:83]
	v_exp_f32_e32 v108, v108
	v_exp_f32_e32 v109, v109
	v_exp_f32_e32 v110, v110
	v_exp_f32_e32 v111, v111
	v_exp_f32_e32 v112, v112
	v_exp_f32_e32 v113, v113
	v_exp_f32_e32 v114, v114
	v_exp_f32_e32 v115, v115
	v_pk_add_f32 v[0:1], v[108:109], v[0:1]
	v_pk_add_f32 v[252:253], v[252:253], v[110:111]
	v_pk_add_f32 v[0:1], v[112:113], v[0:1]
	v_pk_add_f32 v[252:253], v[252:253], v[114:115]
	v_mfma_f32_32x32x64_f8f6f4 v[132:147], v[180:187], v[156:163], v[132:147]
	v_exp_f32_e32 v84, v84
	v_exp_f32_e32 v85, v85
	v_exp_f32_e32 v86, v86
	v_exp_f32_e32 v87, v87
	v_exp_f32_e32 v88, v88
	v_exp_f32_e32 v89, v89
	v_exp_f32_e32 v90, v90
	v_exp_f32_e32 v91, v91
	v_pk_add_f32 v[0:1], v[84:85], v[0:1]
	v_pk_add_f32 v[252:253], v[252:253], v[86:87]
	v_pk_add_f32 v[0:1], v[88:89], v[0:1]
	v_pk_add_f32 v[252:253], v[252:253], v[90:91]
	v_mfma_f32_32x32x64_f8f6f4 v[116:131], v[172:179], v[156:163], v[116:131]
	ds_read_b64 v[182:183], v250
	ds_read_b64 v[176:177], v250 offset:2048
	ds_read_b128 v[178:181], v2
	ds_read_b128 v[172:175], v2 offset:2048
	v_exp_f32_e32 v92, v92
	v_exp_f32_e32 v93, v93
	v_exp_f32_e32 v94, v94
	v_exp_f32_e32 v95, v95
	v_exp_f32_e32 v96, v96
	v_exp_f32_e32 v97, v97
	v_exp_f32_e32 v98, v98
	v_exp_f32_e32 v99, v99
	v_pk_add_f32 v[0:1], v[92:93], v[0:1]
	v_pk_add_f32 v[252:253], v[252:253], v[94:95]
	v_pk_add_f32 v[0:1], v[96:97], v[0:1]
	v_pk_add_f32 v[252:253], v[252:253], v[98:99]
	v_cvt_scalef32_2xpk16_bf6_f32 v[196:201], v[100:115], v[84:99], 1.0
	v_pk_add_f32 v[0:1], v[0:1], v[252:253]
	s_waitcnt lgkmcnt(4)
	v_mfma_f32_32x32x64_f8f6f4 v[132:147], v[242:249], v[164:171], v[132:147]
	s_nop 0
	v_pk_add_f32 v[0:1], v[0:1], v[0:1] op_sel:[0,1] op_sel_hi:[1,0]
	s_nop 0
	v_mov_b32_e32 v1, v0
	s_nop 1
	v_permlane32_swap_b32_e32 v0, v1
	v_mfma_f32_32x32x64_f8f6f4 v[116:131], v[202:209], v[164:171], v[116:131]
	s_waitcnt lgkmcnt(0)
	v_mfma_f32_32x32x64_f8f6f4 v[52:67], v[196:201], v[178:183], v[52:67] cbsz:3 blgp:2
	ds_read_b64 v[102:103], v250 offset:4096
	ds_read_b64 v[96:97], v250 offset:6144
	ds_read_b128 v[98:101], v2 offset:4096
	ds_read_b128 v[92:95], v2 offset:6144
	v_max3_f32 v84, v132, v133, v134
	v_max3_f32 v2, v135, v136, v137
	v_max3_f32 v84, v84, v138, v139
	s_nop 0
	v_max3_f32 v2, v2, v140, v141
	v_max3_f32 v84, v84, v142, v143
	s_nop 0
	v_max3_f32 v2, v2, v144, v145
	v_max3_f32 v84, v84, v146, v147
	v_mfma_f32_32x32x64_f8f6f4 v[36:51], v[196:201], v[172:177], v[36:51] cbsz:3 blgp:2
	v_lshl_add_u32 v105, s9, 13, v233
	v_max3_f32 v84, v84, v116, v117
	v_add_u32_e32 v88, v105, v234
	v_add_u32_e32 v106, v105, v235
	v_max3_f32 v104, v84, v120, v121
	ds_read_b128 v[84:87], v88 offset:49152
	ds_read_b128 v[188:191], v88 offset:53248
	ds_read_b128 v[88:91], v106 offset:49152
	ds_read_b128 v[192:195], v106 offset:53248
	v_add_u32_e32 v106, v105, v236
	v_add_u32_e32 v105, v105, v237
	ds_read_b128 v[180:183], v106 offset:49152
	ds_read_b128 v[172:175], v106 offset:53248
	ds_read_b128 v[184:187], v105 offset:49152
	ds_read_b128 v[176:179], v105 offset:53248
	v_max3_f32 v2, v2, v118, v119
	v_max3_f32 v104, v104, v124, v125
	s_nop 0
	v_max3_f32 v2, v2, v122, v123
	v_max3_f32 v104, v104, v128, v129
	s_nop 0
	v_max3_f32 v2, v2, v126, v127
	s_nop 0
	v_max3_f32 v2, v2, v130, v131
	s_waitcnt lgkmcnt(8)
	v_mfma_f32_32x32x64_f8f6f4 v[20:35], v[196:201], v[98:103], v[20:35] cbsz:3 blgp:2
	v_max_f32_e32 v2, v2, v2
	v_max_f32_e32 v98, v104, v104
	v_max_f32_e32 v2, v98, v2
	v_mov_b32_e32 v98, v2
	s_nop 1
	v_permlane32_swap_b32_e32 v2, v98
	v_max_f32_e32 v98, v98, v98
	v_max_f32_e32 v2, v2, v2
	v_max_f32_e32 v2, v2, v98
	v_cmp_ge_f32_e32 vcc, s0, v2
	s_cmp_eq_u64 vcc, exec
	s_cbranch_scc0 .LBB0_683
	v_mov_b32_e32 v242, 1.0

; template <int C_> __device__ __forceinline__ void fin_chunk(f32x16& p0, f32x16& p1, f32x2& s2, v6i& pf) {
;   f32x16& p = (C_ < 2) ? p0 : p1; constexpr int r0 = 8 * (C_ & 1), g0 = (C_ < 2 ? 0 : 4) + 2 * (C_ & 1);
; #pragma unroll
;   for (int r = r0; r < r0 + 8; ++r) p[r] = __builtin_amdgcn_exp2f(p[r]);
; #pragma unroll
;   for (int r = r0; r < r0 + 8; r += 2) s2 += (f32x2){p[r], p[r + 1]};
;   (void)pf; (void)g0;
; }
; __device__ __forceinline__ void fin_tail(const f32x2& s2, float alpha, float& l_reg) {
;   float ps = s2.x + s2.y;
;   { auto rr = __builtin_amdgcn_permlane32_swap(__float_as_uint(ps), __float_as_uint(ps), false, false);
;     ps = __uint_as_float(rr[0]) + __uint_as_float(rr[1]); }
;   l_reg = l_reg * alpha + ps;
; }
.LBB0_666:
	v_sub_co_u32_e64 v2, s[60:61], s9, 1
	s_and_b64 s[60:61], s[60:61], exec
	v_readfirstlane_b32 s60, v2
	s_cselect_b32 s63, 5, s60
	s_add_i32 s60, s9, 1
	s_cmp_lg_u32 s9, 5
	s_cselect_b32 s62, s60, 0
	s_lshl_b32 s64, s63, 13
	v_add_u32_e32 v2, s64, v239
	v_add_u32_e32 v243, s64, v240
	v_lshl_add_u32 v92, s9, 12, v238
	v_add_u32_e32 v93, v92, v231
	v_add_u32_e32 v92, v92, v232
	ds_read_b128 v[202:205], v93
	ds_read_b128 v[244:247], v93 offset:2048
	ds_read_b128 v[206:209], v92
	ds_read_b128 v[248:251], v92 offset:2048
	v_mfma_f32_32x32x64_f8f6f4 v[100:115], v[84:91], v[148:155], v[68:83]
	v_exp_f32_e32 v132, v132
	v_exp_f32_e32 v133, v133
	v_exp_f32_e32 v134, v134
	v_exp_f32_e32 v135, v135
	v_exp_f32_e32 v136, v136
	v_exp_f32_e32 v137, v137
	v_exp_f32_e32 v138, v138
	v_exp_f32_e32 v139, v139
	v_pk_add_f32 v[196:197], v[132:133], v[134:135]
	v_pk_add_f32 v[252:253], v[136:137], v[138:139]
	v_mfma_f32_32x32x64_f8f6f4 v[84:99], v[188:195], v[148:155], v[68:83]
	v_exp_f32_e32 v140, v140
	v_exp_f32_e32 v141, v141
	v_exp_f32_e32 v142, v142
	v_exp_f32_e32 v143, v143
	v_exp_f32_e32 v144, v144
	v_exp_f32_e32 v145, v145
	v_exp_f32_e32 v146, v146
	v_exp_f32_e32 v147, v147
	v_pk_add_f32 v[188:189], v[140:141], v[196:197]
	v_pk_add_f32 v[252:253], v[252:253], v[142:143]
	v_pk_add_f32 v[188:189], v[144:145], v[188:189]
	v_pk_add_f32 v[252:253], v[252:253], v[146:147]
	v_mfma_f32_32x32x64_f8f6f4 v[100:115], v[180:187], v[156:163], v[100:115]
	v_exp_f32_e32 v116, v116
	v_exp_f32_e32 v117, v117
	v_exp_f32_e32 v118, v118
	v_exp_f32_e32 v119, v119
	v_exp_f32_e32 v120, v120
	v_exp_f32_e32 v121, v121
	v_exp_f32_e32 v122, v122
	v_exp_f32_e32 v123, v123
	v_pk_add_f32 v[180:181], v[116:117], v[188:189]
	v_pk_add_f32 v[252:253], v[252:253], v[118:119]
	v_pk_add_f32 v[184:185], v[120:121], v[180:181]
	v_pk_add_f32 v[252:253], v[252:253], v[122:123]
	v_mfma_f32_32x32x64_f8f6f4 v[84:99], v[172:179], v[156:163], v[84:99]
	ds_read_b64 v[182:183], v243
	ds_read_b64 v[176:177], v243 offset:2048
	ds_read_b128 v[178:181], v2
	ds_read_b128 v[172:175], v2 offset:2048
	v_exp_f32_e32 v124, v124
	v_exp_f32_e32 v125, v125
	v_exp_f32_e32 v126, v126
	v_exp_f32_e32 v127, v127
	v_exp_f32_e32 v128, v128
	v_exp_f32_e32 v129, v129
	v_exp_f32_e32 v130, v130
	v_exp_f32_e32 v131, v131
	v_pk_add_f32 v[184:185], v[124:125], v[184:185]
	v_pk_add_f32 v[252:253], v[252:253], v[126:127]
	v_pk_add_f32 v[184:185], v[128:129], v[184:185]
	v_pk_add_f32 v[252:253], v[252:253], v[130:131]
	v_cvt_scalef32_2xpk16_bf6_f32 v[196:201], v[132:147], v[116:131], 1.0
	v_pk_add_f32 v[184:185], v[184:185], v[252:253]
	s_waitcnt lgkmcnt(4)
	v_mfma_f32_32x32x64_f8f6f4 v[100:115], v[202:209], v[164:171], v[100:115]
	s_nop 0
	v_pk_add_f32 v[130:131], v[184:185], v[184:185] op_sel:[0,1] op_sel_hi:[1,0]
	s_nop 0
	v_mov_b32_e32 v131, v130
	s_nop 1
	v_permlane32_swap_b32_e32 v130, v131
	v_mfma_f32_32x32x64_f8f6f4 v[84:99], v[244:251], v[164:171], v[84:99]
	s_waitcnt lgkmcnt(0)
	v_mfma_f32_32x32x64_f8f6f4 v[52:67], v[196:201], v[178:183], v[52:67] cbsz:3 blgp:2
	ds_read_b64 v[136:137], v243 offset:4096
	ds_read_b64 v[128:129], v243 offset:6144
	ds_read_b128 v[132:135], v2 offset:4096
	ds_read_b128 v[124:127], v2 offset:6144
	v_max3_f32 v116, v100, v101, v102
	v_max3_f32 v2, v103, v104, v105
	v_max3_f32 v116, v116, v106, v107
	s_nop 0
	v_max3_f32 v2, v2, v108, v109
	v_max3_f32 v116, v116, v110, v111
	s_nop 0
	v_max3_f32 v2, v2, v112, v113
	v_max3_f32 v116, v116, v114, v115
	v_mfma_f32_32x32x64_f8f6f4 v[36:51], v[196:201], v[172:177], v[36:51] cbsz:3 blgp:2
	s_lshl_b32 s9, s62, 13
	v_add_u32_e32 v139, s9, v233
	v_max3_f32 v116, v116, v84, v85
	v_add_u32_e32 v120, v139, v234
	v_add_u32_e32 v140, v139, v235
	v_max3_f32 v138, v116, v88, v89
	ds_read_b128 v[116:119], v120 offset:49152
	ds_read_b128 v[188:191], v120 offset:53248
	ds_read_b128 v[120:123], v140 offset:49152
	ds_read_b128 v[192:195], v140 offset:53248
	v_add_u32_e32 v140, v139, v236
	v_add_u32_e32 v139, v139, v237
	ds_read_b128 v[180:183], v140 offset:49152
	ds_read_b128 v[172:175], v140 offset:53248
	ds_read_b128 v[184:187], v139 offset:49152
	ds_read_b128 v[176:179], v139 offset:53248
	v_max3_f32 v2, v2, v86, v87
	v_max3_f32 v138, v138, v92, v93
	s_nop 0
	v_max3_f32 v2, v2, v90, v91
	v_max3_f32 v138, v138, v96, v97
	s_nop 0
	v_max3_f32 v2, v2, v94, v95
	s_nop 0
	v_max3_f32 v2, v2, v98, v99
	s_waitcnt lgkmcnt(8)
	v_mfma_f32_32x32x64_f8f6f4 v[20:35], v[196:201], v[132:137], v[20:35] cbsz:3 blgp:2
	v_max_f32_e32 v2, v2, v2
	v_max_f32_e32 v132, v138, v138
	v_max_f32_e32 v2, v132, v2
	v_mov_b32_e32 v132, v2
	s_nop 1
	v_permlane32_swap_b32_e32 v2, v132
	v_max_f32_e32 v132, v132, v132
	v_max_f32_e32 v2, v2, v2
	v_max_f32_e32 v132, v2, v132
	v_cmp_ge_f32_e32 vcc, s0, v132
	s_cmp_eq_u64 vcc, exec
	v_mov_b32_e32 v2, 1.0
	s_cbranch_scc0 .LBB0_684

; __global__ void __launch_bounds__(NWAVES * 64, 2) fwd(Args args) {
;     ...
;     for (int grp = 0; grp < NGROUP; ++grp) {
;         const int pb = 1 + grp * 7;
;         if (hi <= pb || lo >= pb + 7) continue;
;     ...
;             SEAM(pb + 4);
;         }
;         if (EN(9) && IN(pb + 5)) {
.LBB0_752:
	v_mov_b32_e32 v252, 0x358637bd
	v_mov_b32_e32 v253, 0x1ff
	s_cmp_le_i32 s80, s1
	s_cselect_b64 s[2:3], -1, 0
	s_cmp_lt_i32 s1, s81
	s_cselect_b64 s[8:9], -1, 0
	s_and_b64 s[2:3], s[2:3], s[8:9]
	s_mov_b64 s[28:29], -1
	s_and_b64 vcc, exec, s[2:3]
	s_cbranch_vccnz .LBB0_754
	v_readlane_b32 s1, v255, 0
	s_add_i32 s1, s1, 7
	s_mov_b64 s[28:29], 0

;     ...
;     for (;;) {
;         const bool has_next = S.next(ui + 1, nxt);
;         const char* nA = has_next ? PG8_ABASE(nxt) : cA; const char* nB = has_next ? (const char*)g.Bt + (size_t)nxt.pn * tstepB : cB;
; #pragma unroll 1
;         for (int t = 0; t < nt; t += 2) {
;             const bool last = (t == nt - 2);
;             const char* a1 = cA + (size_t)(t + 1) * kstep;
;             const char* a2 = last ? nA : cA + (size_t)(t + 2) * kstep; const char* b2 = last ? nB : cB + (size_t)(t + 2) * kstep;
;             const char* a3 = a2 + kstep; const char* b3 = b2 + kstep;
;     ...
; #pragma unroll
;         for (int a = 0; a < 2; ++a)
; #pragma unroll
;             for (int b = 0; b < 2; ++b)
; #pragma unroll
;                 for (int m = 0; m < 4; ++m)
; #pragma unroll
;                     for (int n = 0; n < 2; ++n) acc[a][b][m][n] = (f32x4){0.f, 0.f, 0.f, 0.f};
.LBB0_782:
	v_lshl_add_u64 v[6:7], v[148:149], 0, s[52:53]
	v_lshl_add_u64 v[154:155], v[4:5], 0, s[4:5]
	v_mov_b32_e32 v4, 0
	v_lshl_add_u64 v[150:151], v[6:7], 0, v[140:141]
	v_lshl_add_u64 v[152:153], v[6:7], 0, v[142:143]
	s_mov_b32 s38, -2
	s_mov_b64 s[28:29], 0
	v_mov_b32_e32 v5, v4
	v_mov_b64_e32 v[6:7], v[4:5]
	v_mov_b64_e32 v[8:9], v[4:5]
	v_mov_b64_e32 v[10:11], v[4:5]
	v_mov_b64_e32 v[20:21], v[4:5]
	v_mov_b64_e32 v[22:23], v[4:5]
	v_mov_b64_e32 v[24:25], v[4:5]
	v_mov_b64_e32 v[26:27], v[4:5]
	v_mov_b64_e32 v[36:37], v[4:5]
	v_mov_b64_e32 v[38:39], v[4:5]
	v_mov_b64_e32 v[40:41], v[4:5]
	v_mov_b64_e32 v[42:43], v[4:5]
	v_mov_b64_e32 v[52:53], v[4:5]
	v_mov_b64_e32 v[54:55], v[4:5]
	v_mov_b64_e32 v[56:57], v[4:5]
	v_mov_b64_e32 v[58:59], v[4:5]
	v_mov_b64_e32 v[12:13], v[4:5]
	v_mov_b64_e32 v[14:15], v[4:5]
	v_mov_b64_e32 v[16:17], v[4:5]
	v_mov_b64_e32 v[18:19], v[4:5]
	v_mov_b64_e32 v[28:29], v[4:5]
	v_mov_b64_e32 v[30:31], v[4:5]
	v_mov_b64_e32 v[32:33], v[4:5]
	v_mov_b64_e32 v[34:35], v[4:5]
	v_mov_b64_e32 v[44:45], v[4:5]
	v_mov_b64_e32 v[46:47], v[4:5]
	v_mov_b64_e32 v[48:49], v[4:5]
	v_mov_b64_e32 v[50:51], v[4:5]
	v_mov_b64_e32 v[60:61], v[4:5]
	v_mov_b64_e32 v[62:63], v[4:5]
	v_mov_b64_e32 v[64:65], v[4:5]
	v_mov_b64_e32 v[66:67], v[4:5]
	v_mov_b64_e32 v[68:69], v[4:5]
	v_mov_b64_e32 v[70:71], v[4:5]
	v_mov_b64_e32 v[72:73], v[4:5]
	v_mov_b64_e32 v[74:75], v[4:5]
	v_mov_b64_e32 v[84:85], v[4:5]
	v_mov_b64_e32 v[86:87], v[4:5]
	v_mov_b64_e32 v[88:89], v[4:5]
	v_mov_b64_e32 v[90:91], v[4:5]
	v_mov_b64_e32 v[100:101], v[4:5]
	v_mov_b64_e32 v[102:103], v[4:5]
	v_mov_b64_e32 v[104:105], v[4:5]
	v_mov_b64_e32 v[106:107], v[4:5]
	v_mov_b64_e32 v[116:117], v[4:5]
	v_mov_b64_e32 v[118:119], v[4:5]
	v_mov_b64_e32 v[120:121], v[4:5]
	v_mov_b64_e32 v[122:123], v[4:5]
	v_mov_b64_e32 v[76:77], v[4:5]
	v_mov_b64_e32 v[78:79], v[4:5]
	v_mov_b64_e32 v[80:81], v[4:5]
	v_mov_b64_e32 v[82:83], v[4:5]
	v_mov_b64_e32 v[92:93], v[4:5]
	v_mov_b64_e32 v[94:95], v[4:5]
	v_mov_b64_e32 v[96:97], v[4:5]
	v_mov_b64_e32 v[98:99], v[4:5]
	v_mov_b64_e32 v[108:109], v[4:5]
	v_mov_b64_e32 v[110:111], v[4:5]
	v_mov_b64_e32 v[112:113], v[4:5]
	v_mov_b64_e32 v[114:115], v[4:5]
	v_mov_b64_e32 v[124:125], v[4:5]
	v_mov_b64_e32 v[126:127], v[4:5]
	v_mov_b64_e32 v[128:129], v[4:5]
	v_mov_b64_e32 v[130:131], v[4:5]
	v_add_u32_e32 v246, 0x10000, v157
	v_add_u32_e32 v247, 0x14000, v157
	v_add_u32_e32 v248, 0x18000, v157
	v_add_u32_e32 v249, 0x1c000, v157
	.p2align 6

;     ...
;     for (;;) {
;         const bool has_next = S.next(ui + 1, nxt);
;         const char* nA = has_next ? PG8_ABASE(nxt) : cA; const char* nB = has_next ? (const char*)g.Bt + (size_t)nxt.pn * tstepB : cB;
; #pragma unroll 1
;         for (int t = 0; t < nt; t += 2) {
;             const bool last = (t == nt - 2);
;             const char* a1 = cA + (size_t)(t + 1) * kstep;
;             const char* a2 = last ? nA : cA + (size_t)(t + 2) * kstep; const char* b2 = last ? nB : cB + (size_t)(t + 2) * kstep;
;             const char* a3 = a2 + kstep; const char* b3 = b2 + kstep;
;     ...
; #pragma unroll
;         for (int a = 0; a < 2; ++a)
; #pragma unroll
;             for (int b = 0; b < 2; ++b)
; #pragma unroll
;                 for (int m = 0; m < 4; ++m)
; #pragma unroll
;                     for (int n = 0; n < 2; ++n) acc[a][b][m][n] = (f32x4){0.f, 0.f, 0.f, 0.f};
.LBB0_817:
	v_lshl_add_u64 v[6:7], v[180:181], 0, s[52:53]
	v_mov_b32_e32 v36, 0
	v_lshl_add_u64 v[182:183], v[6:7], 0, v[172:173]
	v_lshl_add_u64 v[184:185], v[6:7], 0, v[174:175]
	v_lshl_add_u64 v[186:187], v[4:5], 0, s[4:5]
	s_mov_b32 s42, -2
	s_mov_b64 s[28:29], 0
	v_mov_b32_e32 v37, v36
	v_mov_b64_e32 v[38:39], v[36:37]
	v_mov_b64_e32 v[40:41], v[36:37]
	v_mov_b64_e32 v[42:43], v[36:37]
	v_mov_b64_e32 v[52:53], v[36:37]
	v_mov_b64_e32 v[54:55], v[36:37]
	v_mov_b64_e32 v[56:57], v[36:37]
	v_mov_b64_e32 v[58:59], v[36:37]
	v_mov_b64_e32 v[68:69], v[36:37]
	v_mov_b64_e32 v[70:71], v[36:37]
	v_mov_b64_e32 v[72:73], v[36:37]
	v_mov_b64_e32 v[74:75], v[36:37]
	v_mov_b64_e32 v[84:85], v[36:37]
	v_mov_b64_e32 v[86:87], v[36:37]
	v_mov_b64_e32 v[88:89], v[36:37]
	v_mov_b64_e32 v[90:91], v[36:37]
	v_mov_b64_e32 v[44:45], v[36:37]
	v_mov_b64_e32 v[46:47], v[36:37]
	v_mov_b64_e32 v[48:49], v[36:37]
	v_mov_b64_e32 v[50:51], v[36:37]
	v_mov_b64_e32 v[60:61], v[36:37]
	v_mov_b64_e32 v[62:63], v[36:37]
	v_mov_b64_e32 v[64:65], v[36:37]
	v_mov_b64_e32 v[66:67], v[36:37]
	v_mov_b64_e32 v[76:77], v[36:37]
	v_mov_b64_e32 v[78:79], v[36:37]
	v_mov_b64_e32 v[80:81], v[36:37]
	v_mov_b64_e32 v[82:83], v[36:37]
	v_mov_b64_e32 v[92:93], v[36:37]
	v_mov_b64_e32 v[94:95], v[36:37]
	v_mov_b64_e32 v[96:97], v[36:37]
	v_mov_b64_e32 v[98:99], v[36:37]
	v_mov_b64_e32 v[100:101], v[36:37]
	v_mov_b64_e32 v[102:103], v[36:37]
	v_mov_b64_e32 v[104:105], v[36:37]
	v_mov_b64_e32 v[106:107], v[36:37]
	v_mov_b64_e32 v[116:117], v[36:37]
	v_mov_b64_e32 v[118:119], v[36:37]
	v_mov_b64_e32 v[120:121], v[36:37]
	v_mov_b64_e32 v[122:123], v[36:37]
	v_mov_b64_e32 v[132:133], v[36:37]
	v_mov_b64_e32 v[134:135], v[36:37]
	v_mov_b64_e32 v[136:137], v[36:37]
	v_mov_b64_e32 v[138:139], v[36:37]
	v_mov_b64_e32 v[148:149], v[36:37]
	v_mov_b64_e32 v[150:151], v[36:37]
	v_mov_b64_e32 v[152:153], v[36:37]
	v_mov_b64_e32 v[154:155], v[36:37]
	v_mov_b64_e32 v[108:109], v[36:37]
	v_mov_b64_e32 v[110:111], v[36:37]
	v_mov_b64_e32 v[112:113], v[36:37]
	v_mov_b64_e32 v[114:115], v[36:37]
	v_mov_b64_e32 v[124:125], v[36:37]
	v_mov_b64_e32 v[126:127], v[36:37]
	v_mov_b64_e32 v[128:129], v[36:37]
	v_mov_b64_e32 v[130:131], v[36:37]
	v_mov_b64_e32 v[140:141], v[36:37]
	v_mov_b64_e32 v[142:143], v[36:37]
	v_mov_b64_e32 v[144:145], v[36:37]
	v_mov_b64_e32 v[146:147], v[36:37]
	v_mov_b64_e32 v[156:157], v[36:37]
	v_mov_b64_e32 v[158:159], v[36:37]
	v_mov_b64_e32 v[160:161], v[36:37]
	v_mov_b64_e32 v[162:163], v[36:37]
	v_add_u32_e32 v213, 0x10000, v210
	v_add_u32_e32 v250, 0x14000, v210
	v_add_u32_e32 v251, 0x18000, v210
	.p2align 6

;     ...
;     for (;;) {
;         const bool has_next = S.next(ui + 1, nxt);
;         const char* nA = has_next ? PG8_ABASE(nxt) : cA; const char* nB = has_next ? (const char*)g.Bt + (size_t)nxt.pn * tstepB : cB;
; #pragma unroll 1
;         for (int t = 0; t < nt; t += 2) {
;             const bool last = (t == nt - 2);
;             const char* a1 = cA + (size_t)(t + 1) * kstep;
;             const char* a2 = last ? nA : cA + (size_t)(t + 2) * kstep; const char* b2 = last ? nB : cB + (size_t)(t + 2) * kstep;
;             const char* a3 = a2 + kstep; const char* b3 = b2 + kstep;
;     ...
; #pragma unroll
;         for (int a = 0; a < 2; ++a)
; #pragma unroll
;             for (int b = 0; b < 2; ++b)
; #pragma unroll
;                 for (int m = 0; m < 4; ++m)
; #pragma unroll
;                     for (int n = 0; n < 2; ++n) acc[a][b][m][n] = (f32x4){0.f, 0.f, 0.f, 0.f};
.LBB0_911:
	v_lshl_add_u64 v[6:7], v[148:149], 0, s[52:53]
	v_lshl_add_u64 v[154:155], v[4:5], 0, s[4:5]
	v_mov_b32_e32 v4, 0
	v_lshl_add_u64 v[150:151], v[6:7], 0, v[140:141]
	v_lshl_add_u64 v[152:153], v[6:7], 0, v[142:143]
	s_mov_b32 s58, -2
	s_mov_b64 s[38:39], 0
	v_mov_b32_e32 v5, v4
	v_mov_b64_e32 v[6:7], v[4:5]
	v_mov_b64_e32 v[8:9], v[4:5]
	v_mov_b64_e32 v[10:11], v[4:5]
	v_mov_b64_e32 v[12:13], v[4:5]
	v_mov_b64_e32 v[14:15], v[4:5]
	v_mov_b64_e32 v[16:17], v[4:5]
	v_mov_b64_e32 v[18:19], v[4:5]
	v_mov_b64_e32 v[20:21], v[4:5]
	v_mov_b64_e32 v[22:23], v[4:5]
	v_mov_b64_e32 v[24:25], v[4:5]
	v_mov_b64_e32 v[26:27], v[4:5]
	v_mov_b64_e32 v[28:29], v[4:5]
	v_mov_b64_e32 v[30:31], v[4:5]
	v_mov_b64_e32 v[32:33], v[4:5]
	v_mov_b64_e32 v[34:35], v[4:5]
	v_mov_b64_e32 v[36:37], v[4:5]
	v_mov_b64_e32 v[38:39], v[4:5]
	v_mov_b64_e32 v[40:41], v[4:5]
	v_mov_b64_e32 v[42:43], v[4:5]
	v_mov_b64_e32 v[44:45], v[4:5]
	v_mov_b64_e32 v[46:47], v[4:5]
	v_mov_b64_e32 v[48:49], v[4:5]
	v_mov_b64_e32 v[50:51], v[4:5]
	v_mov_b64_e32 v[52:53], v[4:5]
	v_mov_b64_e32 v[54:55], v[4:5]
	v_mov_b64_e32 v[56:57], v[4:5]
	v_mov_b64_e32 v[58:59], v[4:5]
	v_mov_b64_e32 v[60:61], v[4:5]
	v_mov_b64_e32 v[62:63], v[4:5]
	v_mov_b64_e32 v[64:65], v[4:5]
	v_mov_b64_e32 v[66:67], v[4:5]
	v_mov_b64_e32 v[68:69], v[4:5]
	v_mov_b64_e32 v[70:71], v[4:5]
	v_mov_b64_e32 v[72:73], v[4:5]
	v_mov_b64_e32 v[74:75], v[4:5]
	v_mov_b64_e32 v[76:77], v[4:5]
	v_mov_b64_e32 v[78:79], v[4:5]
	v_mov_b64_e32 v[80:81], v[4:5]
	v_mov_b64_e32 v[82:83], v[4:5]
	v_mov_b64_e32 v[84:85], v[4:5]
	v_mov_b64_e32 v[86:87], v[4:5]
	v_mov_b64_e32 v[88:89], v[4:5]
	v_mov_b64_e32 v[90:91], v[4:5]
	v_mov_b64_e32 v[92:93], v[4:5]
	v_mov_b64_e32 v[94:95], v[4:5]
	v_mov_b64_e32 v[96:97], v[4:5]
	v_mov_b64_e32 v[98:99], v[4:5]
	v_mov_b64_e32 v[100:101], v[4:5]
	v_mov_b64_e32 v[102:103], v[4:5]
	v_mov_b64_e32 v[104:105], v[4:5]
	v_mov_b64_e32 v[106:107], v[4:5]
	v_mov_b64_e32 v[108:109], v[4:5]
	v_mov_b64_e32 v[110:111], v[4:5]
	v_mov_b64_e32 v[112:113], v[4:5]
	v_mov_b64_e32 v[114:115], v[4:5]
	v_mov_b64_e32 v[116:117], v[4:5]
	v_mov_b64_e32 v[118:119], v[4:5]
	v_mov_b64_e32 v[120:121], v[4:5]
	v_mov_b64_e32 v[122:123], v[4:5]
	v_mov_b64_e32 v[124:125], v[4:5]
	v_mov_b64_e32 v[126:127], v[4:5]
	v_mov_b64_e32 v[128:129], v[4:5]
	v_mov_b64_e32 v[130:131], v[4:5]
	v_add_u32_e32 v246, 0x10000, v158
	v_add_u32_e32 v247, 0x14000, v158
	v_add_u32_e32 v248, 0x18000, v158
	v_add_u32_e32 v249, 0x1c000, v158
	.p2align 6

;     ...
;     for (;;) {
;         const bool has_next = S.next(ui + 1, nxt);
;         const char* nA = has_next ? PG8_ABASE(nxt) : cA; const char* nB = has_next ? (const char*)g.Bt + (size_t)nxt.pn * tstepB : cB;
; #pragma unroll 1
;         for (int t = 0; t < nt; t += 2) {
;             const bool last = (t == nt - 2);
;             const char* a1 = cA + (size_t)(t + 1) * kstep;
;             const char* a2 = last ? nA : cA + (size_t)(t + 2) * kstep; const char* b2 = last ? nB : cB + (size_t)(t + 2) * kstep;
;             const char* a3 = a2 + kstep; const char* b3 = b2 + kstep;
;     ...
; #pragma unroll
;         for (int a = 0; a < 2; ++a)
; #pragma unroll
;             for (int b = 0; b < 2; ++b)
; #pragma unroll
;                 for (int m = 0; m < 4; ++m)
; #pragma unroll
;                     for (int n = 0; n < 2; ++n) acc[a][b][m][n] = (f32x4){0.f, 0.f, 0.f, 0.f};
.LBB0_1045:
	v_lshl_add_u64 v[158:159], v[0:1], 0, s[20:21]
	v_mov_b32_e32 v0, 0
	v_lshl_add_u64 v[154:155], v[152:153], 0, v[140:141]
	v_lshl_add_u64 v[156:157], v[152:153], 0, v[142:143]
	s_mov_b32 s38, -2
	s_mov_b64 s[24:25], 0
	v_mov_b32_e32 v1, v0
	v_mov_b64_e32 v[2:3], v[0:1]
	v_mov_b64_e32 v[4:5], v[0:1]
	v_mov_b64_e32 v[6:7], v[0:1]
	v_mov_b64_e32 v[8:9], v[0:1]
	v_mov_b64_e32 v[10:11], v[0:1]
	v_mov_b64_e32 v[12:13], v[0:1]
	v_mov_b64_e32 v[14:15], v[0:1]
	v_mov_b64_e32 v[16:17], v[0:1]
	v_mov_b64_e32 v[18:19], v[0:1]
	v_mov_b64_e32 v[20:21], v[0:1]
	v_mov_b64_e32 v[22:23], v[0:1]
	v_mov_b64_e32 v[24:25], v[0:1]
	v_mov_b64_e32 v[26:27], v[0:1]
	v_mov_b64_e32 v[28:29], v[0:1]
	v_mov_b64_e32 v[30:31], v[0:1]
	v_mov_b64_e32 v[32:33], v[0:1]
	v_mov_b64_e32 v[34:35], v[0:1]
	v_mov_b64_e32 v[36:37], v[0:1]
	v_mov_b64_e32 v[38:39], v[0:1]
	v_mov_b64_e32 v[40:41], v[0:1]
	v_mov_b64_e32 v[42:43], v[0:1]
	v_mov_b64_e32 v[44:45], v[0:1]
	v_mov_b64_e32 v[46:47], v[0:1]
	v_mov_b64_e32 v[48:49], v[0:1]
	v_mov_b64_e32 v[50:51], v[0:1]
	v_mov_b64_e32 v[52:53], v[0:1]
	v_mov_b64_e32 v[54:55], v[0:1]
	v_mov_b64_e32 v[56:57], v[0:1]
	v_mov_b64_e32 v[58:59], v[0:1]
	v_mov_b64_e32 v[60:61], v[0:1]
	v_mov_b64_e32 v[62:63], v[0:1]
	v_mov_b64_e32 v[64:65], v[0:1]
	v_mov_b64_e32 v[66:67], v[0:1]
	v_mov_b64_e32 v[68:69], v[0:1]
	v_mov_b64_e32 v[70:71], v[0:1]
	v_mov_b64_e32 v[72:73], v[0:1]
	v_mov_b64_e32 v[74:75], v[0:1]
	v_mov_b64_e32 v[76:77], v[0:1]
	v_mov_b64_e32 v[78:79], v[0:1]
	v_mov_b64_e32 v[80:81], v[0:1]
	v_mov_b64_e32 v[82:83], v[0:1]
	v_mov_b64_e32 v[84:85], v[0:1]
	v_mov_b64_e32 v[86:87], v[0:1]
	v_mov_b64_e32 v[88:89], v[0:1]
	v_mov_b64_e32 v[90:91], v[0:1]
	v_mov_b64_e32 v[92:93], v[0:1]
	v_mov_b64_e32 v[94:95], v[0:1]
	v_mov_b64_e32 v[96:97], v[0:1]
	v_mov_b64_e32 v[98:99], v[0:1]
	v_mov_b64_e32 v[100:101], v[0:1]
	v_mov_b64_e32 v[102:103], v[0:1]
	v_mov_b64_e32 v[104:105], v[0:1]
	v_mov_b64_e32 v[106:107], v[0:1]
	v_mov_b64_e32 v[108:109], v[0:1]
	v_mov_b64_e32 v[110:111], v[0:1]
	v_mov_b64_e32 v[112:113], v[0:1]
	v_mov_b64_e32 v[114:115], v[0:1]
	v_mov_b64_e32 v[116:117], v[0:1]
	v_mov_b64_e32 v[118:119], v[0:1]
	v_mov_b64_e32 v[120:121], v[0:1]
	v_mov_b64_e32 v[122:123], v[0:1]
	v_mov_b64_e32 v[124:125], v[0:1]
	v_mov_b64_e32 v[126:127], v[0:1]
	v_add_u32_e32 v248, 0x18000, v162
	v_add_u32_e32 v249, 0x1c000, v162
	.p2align 6

;     ...
;     for (;;) {
;         const bool has_next = S.next(ui + 1, nxt);
;         const char* nA = has_next ? PG8_ABASE(nxt) : cA; const char* nB = has_next ? (const char*)g.Bt + (size_t)nxt.pn * tstepB : cB;
; #pragma unroll 1
;         for (int t = 0; t < nt; t += 2) {
;             const bool last = (t == nt - 2);
;             const char* a1 = cA + (size_t)(t + 1) * kstep;
;             const char* a2 = last ? nA : cA + (size_t)(t + 2) * kstep; const char* b2 = last ? nB : cB + (size_t)(t + 2) * kstep;
;             const char* a3 = a2 + kstep; const char* b3 = b2 + kstep;
;     ...
; #pragma unroll
;         for (int a = 0; a < 2; ++a)
; #pragma unroll
;             for (int b = 0; b < 2; ++b)
; #pragma unroll
;                 for (int m = 0; m < 4; ++m)
; #pragma unroll
;                     for (int n = 0; n < 2; ++n) acc[a][b][m][n] = (f32x4){0.f, 0.f, 0.f, 0.f};
.LBB0_1065:
	v_lshl_add_u64 v[158:159], v[0:1], 0, s[16:17]
	v_mov_b32_e32 v0, 0
	v_lshl_add_u64 v[154:155], v[152:153], 0, v[140:141]
	v_lshl_add_u64 v[156:157], v[152:153], 0, v[142:143]
	s_mov_b32 s38, -2
	s_mov_b64 s[18:19], 0
	v_mov_b32_e32 v1, v0
	v_mov_b64_e32 v[2:3], v[0:1]
	v_mov_b64_e32 v[4:5], v[0:1]
	v_mov_b64_e32 v[6:7], v[0:1]
	v_mov_b64_e32 v[16:17], v[0:1]
	v_mov_b64_e32 v[18:19], v[0:1]
	v_mov_b64_e32 v[20:21], v[0:1]
	v_mov_b64_e32 v[22:23], v[0:1]
	v_mov_b64_e32 v[32:33], v[0:1]
	v_mov_b64_e32 v[34:35], v[0:1]
	v_mov_b64_e32 v[36:37], v[0:1]
	v_mov_b64_e32 v[38:39], v[0:1]
	v_mov_b64_e32 v[48:49], v[0:1]
	v_mov_b64_e32 v[50:51], v[0:1]
	v_mov_b64_e32 v[52:53], v[0:1]
	v_mov_b64_e32 v[54:55], v[0:1]
	v_mov_b64_e32 v[8:9], v[0:1]
	v_mov_b64_e32 v[10:11], v[0:1]
	v_mov_b64_e32 v[12:13], v[0:1]
	v_mov_b64_e32 v[14:15], v[0:1]
	v_mov_b64_e32 v[24:25], v[0:1]
	v_mov_b64_e32 v[26:27], v[0:1]
	v_mov_b64_e32 v[28:29], v[0:1]
	v_mov_b64_e32 v[30:31], v[0:1]
	v_mov_b64_e32 v[40:41], v[0:1]
	v_mov_b64_e32 v[42:43], v[0:1]
	v_mov_b64_e32 v[44:45], v[0:1]
	v_mov_b64_e32 v[46:47], v[0:1]
	v_mov_b64_e32 v[56:57], v[0:1]
	v_mov_b64_e32 v[58:59], v[0:1]
	v_mov_b64_e32 v[60:61], v[0:1]
	v_mov_b64_e32 v[62:63], v[0:1]
	v_mov_b64_e32 v[64:65], v[0:1]
	v_mov_b64_e32 v[66:67], v[0:1]
	v_mov_b64_e32 v[68:69], v[0:1]
	v_mov_b64_e32 v[70:71], v[0:1]
	v_mov_b64_e32 v[80:81], v[0:1]
	v_mov_b64_e32 v[82:83], v[0:1]
	v_mov_b64_e32 v[84:85], v[0:1]
	v_mov_b64_e32 v[86:87], v[0:1]
	v_mov_b64_e32 v[96:97], v[0:1]
	v_mov_b64_e32 v[98:99], v[0:1]
	v_mov_b64_e32 v[100:101], v[0:1]
	v_mov_b64_e32 v[102:103], v[0:1]
	v_mov_b64_e32 v[112:113], v[0:1]
	v_mov_b64_e32 v[114:115], v[0:1]
	v_mov_b64_e32 v[116:117], v[0:1]
	v_mov_b64_e32 v[118:119], v[0:1]
	v_mov_b64_e32 v[72:73], v[0:1]
	v_mov_b64_e32 v[74:75], v[0:1]
	v_mov_b64_e32 v[76:77], v[0:1]
	v_mov_b64_e32 v[78:79], v[0:1]
	v_mov_b64_e32 v[88:89], v[0:1]
	v_mov_b64_e32 v[90:91], v[0:1]
	v_mov_b64_e32 v[92:93], v[0:1]
	v_mov_b64_e32 v[94:95], v[0:1]
	v_mov_b64_e32 v[104:105], v[0:1]
	v_mov_b64_e32 v[106:107], v[0:1]
	v_mov_b64_e32 v[108:109], v[0:1]
	v_mov_b64_e32 v[110:111], v[0:1]
	v_mov_b64_e32 v[120:121], v[0:1]
	v_mov_b64_e32 v[122:123], v[0:1]
	v_mov_b64_e32 v[124:125], v[0:1]
	v_mov_b64_e32 v[126:127], v[0:1]
	v_add_u32_e32 v248, 0x18000, v162
	v_add_u32_e32 v249, 0x1c000, v162
	.p2align 6

;     ...
;     for (;;) {
;         const bool has_next = S.next(ui + 1, nxt);
;         const char* nA = has_next ? PG8_ABASE(nxt) : cA; const char* nB = has_next ? (const char*)g.Bt + (size_t)nxt.pn * tstepB : cB;
; #pragma unroll 1
;         for (int t = 0; t < nt; t += 2) {
;             const bool last = (t == nt - 2);
;             const char* a1 = cA + (size_t)(t + 1) * kstep;
;             const char* a2 = last ? nA : cA + (size_t)(t + 2) * kstep; const char* b2 = last ? nB : cB + (size_t)(t + 2) * kstep;
;             const char* a3 = a2 + kstep; const char* b3 = b2 + kstep;
;     ...
; #pragma unroll
;         for (int a = 0; a < 2; ++a)
; #pragma unroll
;             for (int b = 0; b < 2; ++b)
; #pragma unroll
;                 for (int m = 0; m < 4; ++m)
; #pragma unroll
;                     for (int n = 0; n < 2; ++n) acc[a][b][m][n] = (f32x4){0.f, 0.f, 0.f, 0.f};
.LBB0_1147:
	v_lshl_add_u64 v[158:159], v[0:1], 0, s[16:17]
	v_mov_b32_e32 v0, 0
	v_lshl_add_u64 v[154:155], v[152:153], 0, v[140:141]
	v_lshl_add_u64 v[156:157], v[152:153], 0, v[142:143]
	s_mov_b32 s20, -2
	s_mov_b64 s[18:19], 0
	v_mov_b32_e32 v1, v0
	v_mov_b64_e32 v[2:3], v[0:1]
	v_mov_b64_e32 v[4:5], v[0:1]
	v_mov_b64_e32 v[6:7], v[0:1]
	v_mov_b64_e32 v[16:17], v[0:1]
	v_mov_b64_e32 v[18:19], v[0:1]
	v_mov_b64_e32 v[20:21], v[0:1]
	v_mov_b64_e32 v[22:23], v[0:1]
	v_mov_b64_e32 v[32:33], v[0:1]
	v_mov_b64_e32 v[34:35], v[0:1]
	v_mov_b64_e32 v[36:37], v[0:1]
	v_mov_b64_e32 v[38:39], v[0:1]
	v_mov_b64_e32 v[48:49], v[0:1]
	v_mov_b64_e32 v[50:51], v[0:1]
	v_mov_b64_e32 v[52:53], v[0:1]
	v_mov_b64_e32 v[54:55], v[0:1]
	v_mov_b64_e32 v[8:9], v[0:1]
	v_mov_b64_e32 v[10:11], v[0:1]
	v_mov_b64_e32 v[12:13], v[0:1]
	v_mov_b64_e32 v[14:15], v[0:1]
	v_mov_b64_e32 v[24:25], v[0:1]
	v_mov_b64_e32 v[26:27], v[0:1]
	v_mov_b64_e32 v[28:29], v[0:1]
	v_mov_b64_e32 v[30:31], v[0:1]
	v_mov_b64_e32 v[40:41], v[0:1]
	v_mov_b64_e32 v[42:43], v[0:1]
	v_mov_b64_e32 v[44:45], v[0:1]
	v_mov_b64_e32 v[46:47], v[0:1]
	v_mov_b64_e32 v[56:57], v[0:1]
	v_mov_b64_e32 v[58:59], v[0:1]
	v_mov_b64_e32 v[60:61], v[0:1]
	v_mov_b64_e32 v[62:63], v[0:1]
	v_mov_b64_e32 v[64:65], v[0:1]
	v_mov_b64_e32 v[66:67], v[0:1]
	v_mov_b64_e32 v[68:69], v[0:1]
	v_mov_b64_e32 v[70:71], v[0:1]
	v_mov_b64_e32 v[80:81], v[0:1]
	v_mov_b64_e32 v[82:83], v[0:1]
	v_mov_b64_e32 v[84:85], v[0:1]
	v_mov_b64_e32 v[86:87], v[0:1]
	v_mov_b64_e32 v[96:97], v[0:1]
	v_mov_b64_e32 v[98:99], v[0:1]
	v_mov_b64_e32 v[100:101], v[0:1]
	v_mov_b64_e32 v[102:103], v[0:1]
	v_mov_b64_e32 v[112:113], v[0:1]
	v_mov_b64_e32 v[114:115], v[0:1]
	v_mov_b64_e32 v[116:117], v[0:1]
	v_mov_b64_e32 v[118:119], v[0:1]
	v_mov_b64_e32 v[72:73], v[0:1]
	v_mov_b64_e32 v[74:75], v[0:1]
	v_mov_b64_e32 v[76:77], v[0:1]
	v_mov_b64_e32 v[78:79], v[0:1]
	v_mov_b64_e32 v[88:89], v[0:1]
	v_mov_b64_e32 v[90:91], v[0:1]
	v_mov_b64_e32 v[92:93], v[0:1]
	v_mov_b64_e32 v[94:95], v[0:1]
	v_mov_b64_e32 v[104:105], v[0:1]
	v_mov_b64_e32 v[106:107], v[0:1]
	v_mov_b64_e32 v[108:109], v[0:1]
	v_mov_b64_e32 v[110:111], v[0:1]
	v_mov_b64_e32 v[120:121], v[0:1]
	v_mov_b64_e32 v[122:123], v[0:1]
	v_mov_b64_e32 v[124:125], v[0:1]
	v_mov_b64_e32 v[126:127], v[0:1]
	v_add_u32_e32 v248, 0x18000, v162
	v_add_u32_e32 v249, 0x1c000, v162
	.p2align 6
